# attn task queue: task index broadcast through ds_write/ds_read instead of FLAT LDS-aperture accesses
# speedup vs baseline: 1.0039x; 1.0039x over previous
.LBB0_222:
	s_or_b64 exec, exec, s[6:7]
	s_waitcnt vmcnt(0)
	v_readfirstlane_b32 s0, v3
	s_mov_b64 s[6:7], src_shared_base
	s_nop 0
	v_add_u32_e32 v0, s0, v0
	s_add_i32 s0, 0, 0x24000
	s_cmp_lg_u32 s0, -1
	s_cselect_b32 s0, s0, 0
	s_cselect_b32 s6, s7, 0
	v_mov_b32_e32 v4, s0
	v_mov_b32_e32 v5, s6
	ds_write_b32 v4, v0
	s_waitcnt lgkmcnt(0)
.LBB0_223:
	s_or_b64 exec, exec, s[4:5]
	s_add_i32 s0, 0, 0x24000
	s_mov_b64 s[4:5], src_shared_base
	s_cmp_lg_u32 s0, -1
	s_cselect_b32 s0, s0, 0
	s_cselect_b32 s4, s5, 0
	v_mov_b32_e32 v4, s0
	v_mov_b32_e32 v5, s4
	s_waitcnt lgkmcnt(0)
	s_barrier
	ds_read_b32 v4, v4
	s_movk_i32 s0, 0x548
	s_mov_b64 s[4:5], -1
	s_waitcnt lgkmcnt(0)
	s_barrier
	v_cmp_gt_i32_e32 vcc, s0, v4
	s_mov_b64 s[6:7], exec
	v_writelane_b32 v254, s6, 48
	s_nop 1
	v_writelane_b32 v254, s7, 49
	s_and_b64 s[6:7], s[6:7], vcc
	s_mov_b64 exec, s[6:7]
	s_cbranch_execz .LBB0_218
	v_ashrrev_i32_e32 v5, 31, v4
	s_getpc_b64 s[4:5]
	s_add_u32 s4, s4, _ZL5g_tab@rel32@lo+8
	s_addc_u32 s5, s5, _ZL5g_tab@rel32@hi+16
	v_lshl_add_u64 v[4:5], v[4:5], 2, s[4:5]
	global_load_dword v10, v[4:5], off
	s_mov_b32 s0, 0x10000
	s_waitcnt vmcnt(0)
	v_cmp_gt_u32_e64 s[4:5], s0, v10
	s_nop 1
	v_writelane_b32 v254, s4, 50
	s_mov_b32 s0, 0xffff
	v_cmp_lt_u32_e64 s[6:7], s0, v10
	v_writelane_b32 v254, s5, 51
	v_cmp_ne_u32_sdwa s[4:5], v10, v206 src0_sel:WORD_1 src1_sel:DWORD
	v_writelane_b32 v254, s6, 52
	v_and_b32_e32 v12, 0xffff, v10
	s_and_b64 s[4:5], s[6:7], s[4:5]
	v_writelane_b32 v254, s7, 53
	s_and_saveexec_b64 s[6:7], s[4:5]
	s_xor_b64 s[6:7], exec, s[6:7]
	v_writelane_b32 v254, s6, 54
	s_nop 1
	v_writelane_b32 v254, s7, 55
	s_cbranch_execz .LBB0_314
	v_cmp_gt_i16_sdwa s[6:7], v10, v206 src0_sel:WORD_1 src1_sel:DWORD
	s_mov_b64 s[8:9], 0
	s_mov_b64 s[4:5], 0
	s_and_saveexec_b64 s[10:11], s[6:7]
	s_xor_b64 s[6:7], exec, s[10:11]
	s_cbranch_execz .LBB0_228
	v_mov_b32_e32 v0, 3
	v_cmp_ne_u16_sdwa s[4:5], v10, v0 src0_sel:WORD_1 src1_sel:DWORD
	s_and_b64 s[8:9], s[4:5], exec
	s_mov_b64 s[4:5], exec
	s_andn2_saveexec_b64 s[6:7], s[6:7]
	s_cbranch_execnz .LBB0_229
